# attention QK^T (mask-free copy): every K fragment has its own buffer, ten reads requested at the top of the tile
# baseline (speedup 1.0000x reference)
.Latt_top_done:
	s_sub_i32 s0, s39, 31
	s_cmp_gt_u32 s0, s41
	s_cbranch_scc1 .LBB0_235
	s_cmp_gt_u32 s39, s37
	s_cbranch_scc1 .Latt_diag
	v_add_u32_e32 v168, s43, v178
	ds_read_b128 v[196:199], v168
	ds_read_b128 v[200:203], v168 offset:4352
	ds_read_b128 v[214:217], v168 offset:64
	ds_read_b128 v[218:221], v168 offset:4416
	ds_read_b128 v[222:225], v168 offset:128
	ds_read_b128 v[226:229], v168 offset:4480
	ds_read_b128 v[234:237], v168 offset:192
	ds_read_b128 v[230:233], v168 offset:4544
	ds_read_b128 v[206:209], v168 offset:8704
	ds_read_b128 v[210:213], v168 offset:13056
	v_cvt_f32_i32_e32 v238, v194
	s_waitcnt lgkmcnt(9)
	v_mfma_f32_16x16x32_bf16 v[196:199], v[196:199], v[240:243], 0
	s_waitcnt lgkmcnt(8)
	v_mfma_f32_16x16x32_bf16 v[200:203], v[200:203], v[240:243], 0
	s_waitcnt lgkmcnt(7)
	v_mfma_f32_16x16x32_bf16 v[196:199], v[214:217], v[244:247], v[196:199]
	ds_read_b128 v[214:217], v168 offset:8768
	s_waitcnt lgkmcnt(7)
	v_mfma_f32_16x16x32_bf16 v[200:203], v[218:221], v[244:247], v[200:203]
	ds_read_b128 v[218:221], v168 offset:13120
	s_waitcnt lgkmcnt(7)
	v_mfma_f32_16x16x32_bf16 v[196:199], v[222:225], v[248:251], v[196:199]
	ds_read_b128 v[222:225], v168 offset:8832
	s_waitcnt lgkmcnt(7)
	v_mfma_f32_16x16x32_bf16 v[200:203], v[226:229], v[248:251], v[200:203]
	ds_read_b128 v[226:229], v168 offset:13184
	s_waitcnt lgkmcnt(7)
	v_mfma_f32_16x16x32_bf16 v[234:237], v[234:237], v[252:255], v[196:199]
	s_waitcnt lgkmcnt(6)
	v_mfma_f32_16x16x32_bf16 v[202:205], v[230:233], v[252:255], v[200:203]
	ds_read_b128 v[230:233], v168 offset:13248
	s_nop 1
	s_nop 0
	s_nop 0
	v_mul_f32_e64 v197, -s86, v238
	v_fmamk_f32 v196, v234, 0x3e0293ee, v197
	v_add_f32_e32 v198, 0, v196
	v_fmamk_f32 v196, v235, 0x3e0293ee, v197
	v_fmamk_f32 v200, v236, 0x3e0293ee, v197
	v_fmamk_f32 v201, v237, 0x3e0293ee, v197
	s_waitcnt lgkmcnt(6)
	v_mfma_f32_16x16x32_bf16 v[206:209], v[206:209], v[148:151], 0
	v_add_f32_e32 v199, s86, v196
	s_waitcnt lgkmcnt(5)
	v_mfma_f32_16x16x32_bf16 v[210:213], v[210:213], v[148:151], 0
	v_add_f32_e32 v200, s88, v200
	v_add_f32_e32 v201, s89, v201
	s_waitcnt lgkmcnt(4)
	v_mfma_f32_16x16x32_bf16 v[206:209], v[214:217], v[152:155], v[206:209]
	ds_read_b128 v[214:217], v168 offset:8896
	v_fmamk_f32 v202, v202, 0x3e0293ee, v197
	v_fmamk_f32 v203, v203, 0x3e0293ee, v197
	v_max3_f32 v196, v198, s33, v199
	v_add_f32_e32 v202, s87, v202
	v_add_f32_e32 v203, s90, v203
	v_fmamk_f32 v204, v204, 0x3e0293ee, v197
	v_fmamk_f32 v205, v205, 0x3e0293ee, v197
	v_max3_f32 v196, v196, v200, v201
	v_add_f32_e32 v204, v161, v204
	v_add_f32_e32 v205, v193, v205
	s_waitcnt lgkmcnt(4)
	v_mfma_f32_16x16x32_bf16 v[210:213], v[218:221], v[152:155], v[210:213]
	v_max3_f32 v196, v196, v202, v203
	s_waitcnt lgkmcnt(3)
	v_mfma_f32_16x16x32_bf16 v[206:209], v[222:225], v[156:159], v[206:209]
	v_max3_f32 v196, v196, v204, v205
	v_mov_b32_e32 v234, v196
	s_nop 1
	v_permlane16_swap_b32_e32 v196, v234
	v_max_f32_e32 v234, v234, v234
	v_max_f32_e32 v196, v196, v196
	s_waitcnt lgkmcnt(2)
	v_mfma_f32_16x16x32_bf16 v[210:213], v[226:229], v[156:159], v[210:213]
	v_max_f32_e32 v196, v196, v234
	v_mov_b32_e32 v168, v196
	s_nop 1
	v_permlane32_swap_b32_e32 v196, v168
	s_waitcnt lgkmcnt(0)
	v_mfma_f32_16x16x32_bf16 v[206:209], v[214:217], v[184:187], v[206:209]
	v_max3_f32 v196, v167, v196, v168
	v_sub_f32_e32 v167, v167, v196
	v_exp_f32_e32 v167, v167
	v_mfma_f32_16x16x32_bf16 v[210:213], v[230:233], v[184:187], v[210:213]
	s_nop 2
	s_nop 0
	v_fmamk_f32 v168, v206, 0x3e0293ee, v197
	v_add_f32_e32 v206, 0, v168
	v_fmamk_f32 v168, v207, 0x3e0293ee, v197
	v_add_f32_e32 v207, s86, v168
	v_fmamk_f32 v208, v208, 0x3e0293ee, v197
	v_fmamk_f32 v209, v209, 0x3e0293ee, v197
	v_add_f32_e32 v208, s88, v208
	v_add_f32_e32 v209, s89, v209
	v_fmamk_f32 v210, v210, 0x3e0293ee, v197
	v_fmamk_f32 v211, v211, 0x3e0293ee, v197
	v_max3_f32 v168, v206, s33, v207
	v_add_f32_e32 v210, s87, v210
	v_add_f32_e32 v211, s90, v211
	v_fmamk_f32 v212, v212, 0x3e0293ee, v197
	v_fmac_f32_e32 v197, 0x3e0293ee, v213
	v_max3_f32 v168, v168, v208, v209
	v_add_f32_e32 v212, v161, v212
	v_add_f32_e32 v213, v193, v197
	v_max3_f32 v168, v168, v210, v211
	v_max3_f32 v168, v168, v212, v213
	v_mov_b32_e32 v197, v168
	s_nop 1
	v_permlane16_swap_b32_e32 v168, v197
	v_max_f32_e32 v197, v197, v197
	v_max_f32_e32 v168, v168, v168
	v_max_f32_e32 v168, v168, v197
	v_mov_b32_e32 v197, v168
	s_nop 1
	v_permlane32_swap_b32_e32 v168, v197
	v_max3_f32 v197, v166, v168, v197
	v_sub_f32_e32 v166, v166, v197
	v_exp_f32_e32 v166, v166
	s_branch .Latt_s1done
